# streaming cache policy: nt hint on the 16 final-output stores of P13 (written once, never re-read)
# speedup vs baseline: 1.0018x; 1.0018x over previous
; #define GAS __attribute__((address_space(1)))
; __global__ void __launch_bounds__(NTHREADS, 2) fwd(Args a) {
;     ...
;         while (row < MLAT) {
;             const int nrow = row + NGW;
;             if (nrow < MLAT) loadrow(nrow, xn, yn);
;             GAS f32x4* op = (GAS f32x4*)(a.out + (size_t)row * D) + lane;
;             float s = 0.f;
; #pragma unroll
;             for (int q = 0; q < 16; ++q) { v[q] = (f32x4){bflo(xv[q].x), bfhi(xv[q].x), bflo(xv[q].y), bfhi(xv[q].y)} + (f32x4){bflo(yv[q].x), bfhi(yv[q].x), bflo(yv[q].y), bfhi(yv[q].y)}; s += (v[q].x * v[q].x + v[q].y * v[q].y) + (v[q].z * v[q].z + v[q].w * v[q].w); }
.LBB0_1271:
	s_waitcnt vmcnt(23)
	v_lshlrev_b32_e32 v158, 16, v152
	v_and_b32_e32 v159, 0xffff0000, v152
	v_lshlrev_b32_e32 v160, 16, v153
	v_and_b32_e32 v161, 0xffff0000, v153
	s_waitcnt vmcnt(3)
	v_lshlrev_b32_e32 v152, 16, v154
	v_and_b32_e32 v153, 0xffff0000, v154
	v_lshlrev_b32_e32 v154, 16, v155
	v_and_b32_e32 v155, 0xffff0000, v155
	v_pk_add_f32 v[152:153], v[158:159], v[152:153]
	v_pk_add_f32 v[154:155], v[160:161], v[154:155]
	v_pk_mul_f32 v[160:161], v[152:153], v[152:153]
	v_pk_mul_f32 v[158:159], v[154:155], v[154:155]
	s_waitcnt vmcnt(0)
	v_lshlrev_b32_e32 v176, 16, v98
	v_pk_mov_b32 v[162:163], v[160:161], v[158:159] op_sel:[1,0]
	v_mov_b32_e32 v161, v159
	v_pk_add_f32 v[158:159], v[162:163], v[160:161]
	v_lshlrev_b32_e32 v160, 16, v148
	v_and_b32_e32 v161, 0xffff0000, v148
	v_lshlrev_b32_e32 v162, 16, v149
	v_and_b32_e32 v163, 0xffff0000, v149
	v_lshlrev_b32_e32 v148, 16, v156
	v_and_b32_e32 v149, 0xffff0000, v156
	v_lshlrev_b32_e32 v156, 16, v157
	v_and_b32_e32 v157, 0xffff0000, v157
	v_pk_add_f32 v[148:149], v[160:161], v[148:149]
	v_pk_add_f32 v[156:157], v[162:163], v[156:157]
	v_pk_mul_f32 v[162:163], v[148:149], v[148:149]
	v_pk_mul_f32 v[160:161], v[156:157], v[156:157]
	v_pk_add_f32 v[158:159], v[158:159], v[158:159] op_sel:[0,1] op_sel_hi:[1,0]
	v_pk_mov_b32 v[174:175], v[162:163], v[160:161] op_sel:[1,0]
	v_mov_b32_e32 v163, v161
	v_pk_add_f32 v[160:161], v[174:175], v[162:163]
	v_lshlrev_b32_e32 v162, 16, v144
	v_and_b32_e32 v163, 0xffff0000, v144
	v_lshlrev_b32_e32 v144, 16, v145
	v_and_b32_e32 v145, 0xffff0000, v145
	v_lshlrev_b32_e32 v174, 16, v150
	v_and_b32_e32 v175, 0xffff0000, v150
	v_lshlrev_b32_e32 v150, 16, v151
	v_and_b32_e32 v151, 0xffff0000, v151
	v_pk_add_f32 v[144:145], v[144:145], v[150:151]
	v_pk_add_f32 v[150:151], v[162:163], v[174:175]
	v_lshlrev_b32_e32 v162, 16, v142
	v_and_b32_e32 v163, 0xffff0000, v142
	v_lshlrev_b32_e32 v142, 16, v143
	v_and_b32_e32 v143, 0xffff0000, v143
	v_lshlrev_b32_e32 v174, 16, v146
	v_and_b32_e32 v175, 0xffff0000, v146
	v_lshlrev_b32_e32 v146, 16, v147
	v_and_b32_e32 v147, 0xffff0000, v147
	v_pk_add_f32 v[142:143], v[142:143], v[146:147]
	v_pk_add_f32 v[146:147], v[162:163], v[174:175]
	v_pk_add_f32 v[160:161], v[160:161], v[160:161] op_sel:[0,1] op_sel_hi:[1,0]
	v_mul_f32_e32 v162, v146, v146
	v_mul_f32_e32 v163, v147, v147
	v_mov_b32_e32 v159, v162
	v_mov_b32_e32 v161, v163
	v_pk_add_f32 v[158:159], v[158:159], v[160:161]
	v_mul_f32_e32 v160, v151, v151
	v_mul_f32_e32 v162, v145, v145
	v_mul_f32_e32 v164, v142, v142
	v_mul_f32_e32 v173, v143, v143
	v_pk_fma_f32 v[160:161], v[150:151], v[150:151], v[160:161] op_sel_hi:[1,1,0]
	v_pk_fma_f32 v[162:163], v[144:145], v[144:145], v[162:163] op_sel_hi:[1,1,0]
	v_mov_b32_e32 v161, v164
	v_mov_b32_e32 v163, v173
	v_pk_add_f32 v[160:161], v[160:161], v[162:163]
	v_lshlrev_b32_e32 v162, 16, v137
	v_pk_add_f32 v[158:159], v[158:159], v[160:161]
	v_lshlrev_b32_e32 v160, 16, v136
	v_and_b32_e32 v161, 0xffff0000, v136
	v_and_b32_e32 v163, 0xffff0000, v137
	v_lshlrev_b32_e32 v136, 16, v140
	v_and_b32_e32 v137, 0xffff0000, v140
	v_lshlrev_b32_e32 v140, 16, v141
	v_and_b32_e32 v141, 0xffff0000, v141
	v_pk_add_f32 v[136:137], v[160:161], v[136:137]
	v_pk_add_f32 v[140:141], v[162:163], v[140:141]
	v_pk_mul_f32 v[162:163], v[136:137], v[136:137]
	v_pk_mul_f32 v[160:161], v[140:141], v[140:141]
	v_pk_add_f32 v[158:159], v[158:159], v[158:159] op_sel:[0,1] op_sel_hi:[1,0]
	v_pk_mov_b32 v[174:175], v[162:163], v[160:161] op_sel:[1,0]
	v_mov_b32_e32 v163, v161
	v_pk_add_f32 v[160:161], v[174:175], v[162:163]
	v_lshlrev_b32_e32 v162, 16, v132
	v_and_b32_e32 v163, 0xffff0000, v132
	v_lshlrev_b32_e32 v132, 16, v133
	v_and_b32_e32 v133, 0xffff0000, v133
	v_lshlrev_b32_e32 v174, 16, v138
	v_and_b32_e32 v175, 0xffff0000, v138
	v_lshlrev_b32_e32 v138, 16, v139
	v_and_b32_e32 v139, 0xffff0000, v139
	v_pk_add_f32 v[132:133], v[132:133], v[138:139]
	v_pk_add_f32 v[138:139], v[162:163], v[174:175]
	v_lshlrev_b32_e32 v162, 16, v130
	v_and_b32_e32 v163, 0xffff0000, v130
	v_lshlrev_b32_e32 v130, 16, v131
	v_and_b32_e32 v131, 0xffff0000, v131
	v_lshlrev_b32_e32 v174, 16, v134
	v_and_b32_e32 v175, 0xffff0000, v134
	v_lshlrev_b32_e32 v134, 16, v135
	v_and_b32_e32 v135, 0xffff0000, v135
	v_pk_add_f32 v[130:131], v[130:131], v[134:135]
	v_pk_add_f32 v[134:135], v[162:163], v[174:175]
	v_pk_add_f32 v[160:161], v[160:161], v[160:161] op_sel:[0,1] op_sel_hi:[1,0]
	v_mul_f32_e32 v162, v134, v134
	v_mul_f32_e32 v163, v135, v135
	v_mov_b32_e32 v159, v162
	v_mov_b32_e32 v161, v163
	v_pk_add_f32 v[158:159], v[158:159], v[160:161]
	v_mul_f32_e32 v160, v139, v139
	v_mul_f32_e32 v162, v133, v133
	v_mul_f32_e32 v164, v130, v130
	v_mul_f32_e32 v173, v131, v131
	v_pk_fma_f32 v[160:161], v[138:139], v[138:139], v[160:161] op_sel_hi:[1,1,0]
	v_pk_fma_f32 v[162:163], v[132:133], v[132:133], v[162:163] op_sel_hi:[1,1,0]
	v_mov_b32_e32 v161, v164
	v_mov_b32_e32 v163, v173
	v_pk_add_f32 v[160:161], v[160:161], v[162:163]
	v_lshlrev_b32_e32 v162, 16, v125
	v_pk_add_f32 v[158:159], v[158:159], v[160:161]
	v_lshlrev_b32_e32 v160, 16, v124
	v_and_b32_e32 v161, 0xffff0000, v124
	v_and_b32_e32 v163, 0xffff0000, v125
	v_lshlrev_b32_e32 v124, 16, v128
	v_and_b32_e32 v125, 0xffff0000, v128
	v_lshlrev_b32_e32 v128, 16, v129
	v_and_b32_e32 v129, 0xffff0000, v129
	v_pk_add_f32 v[124:125], v[160:161], v[124:125]
	v_pk_add_f32 v[128:129], v[162:163], v[128:129]
	v_pk_mul_f32 v[162:163], v[124:125], v[124:125]
	v_pk_mul_f32 v[160:161], v[128:129], v[128:129]
	v_pk_add_f32 v[158:159], v[158:159], v[158:159] op_sel:[0,1] op_sel_hi:[1,0]
	v_pk_mov_b32 v[174:175], v[162:163], v[160:161] op_sel:[1,0]
; #define GAS __attribute__((address_space(1)))
; __global__ void __launch_bounds__(NTHREADS, 2) fwd(Args a) {
;     ...
;             for (int q = 0; q < 16; ++q) { v[q] = (f32x4){bflo(xv[q].x), bfhi(xv[q].x), bflo(xv[q].y), bfhi(xv[q].y)} + (f32x4){bflo(yv[q].x), bfhi(yv[q].x), bflo(yv[q].y), bfhi(yv[q].y)}; s += (v[q].x * v[q].x + v[q].y * v[q].y) + (v[q].z * v[q].z + v[q].w * v[q].w); }
;             const float rstd = 1.0f / sqrtf(wave_sum(s) * (1.0f / D) + 1e-6f);
;     ...
;             for (int q = 0; q < 16; ++q) { const f32x4 gg = *(const GAS f32x4*)(fg + 4 * lane + 256 * q); op[64 * q] = v[q] * rstd * gg; }
	v_mov_b32_e32 v163, v161
	v_pk_add_f32 v[160:161], v[174:175], v[162:163]
	v_lshlrev_b32_e32 v162, 16, v120
	v_and_b32_e32 v163, 0xffff0000, v120
	v_lshlrev_b32_e32 v120, 16, v121
	v_and_b32_e32 v121, 0xffff0000, v121
	v_lshlrev_b32_e32 v174, 16, v126
	v_and_b32_e32 v175, 0xffff0000, v126
	v_lshlrev_b32_e32 v126, 16, v127
	v_and_b32_e32 v127, 0xffff0000, v127
	v_pk_add_f32 v[120:121], v[120:121], v[126:127]
	v_pk_add_f32 v[126:127], v[162:163], v[174:175]
	v_lshlrev_b32_e32 v162, 16, v118
	v_and_b32_e32 v163, 0xffff0000, v118
	v_lshlrev_b32_e32 v118, 16, v119
	v_and_b32_e32 v119, 0xffff0000, v119
	v_lshlrev_b32_e32 v174, 16, v122
	v_and_b32_e32 v175, 0xffff0000, v122
	v_lshlrev_b32_e32 v122, 16, v123
	v_and_b32_e32 v123, 0xffff0000, v123
	v_pk_add_f32 v[118:119], v[118:119], v[122:123]
	v_pk_add_f32 v[122:123], v[162:163], v[174:175]
	v_pk_add_f32 v[160:161], v[160:161], v[160:161] op_sel:[0,1] op_sel_hi:[1,0]
	v_mul_f32_e32 v162, v122, v122
	v_mul_f32_e32 v163, v123, v123
	v_mov_b32_e32 v159, v162
	v_mov_b32_e32 v161, v163
	v_pk_add_f32 v[158:159], v[158:159], v[160:161]
	v_mul_f32_e32 v160, v127, v127
	v_mul_f32_e32 v162, v121, v121
	v_mul_f32_e32 v164, v118, v118
	v_mul_f32_e32 v173, v119, v119
	v_pk_fma_f32 v[160:161], v[126:127], v[126:127], v[160:161] op_sel_hi:[1,1,0]
	v_pk_fma_f32 v[162:163], v[120:121], v[120:121], v[162:163] op_sel_hi:[1,1,0]
	v_mov_b32_e32 v161, v164
	v_mov_b32_e32 v163, v173
	v_pk_add_f32 v[160:161], v[160:161], v[162:163]
	v_lshlrev_b32_e32 v162, 16, v113
	v_pk_add_f32 v[158:159], v[158:159], v[160:161]
	v_lshlrev_b32_e32 v160, 16, v112
	v_and_b32_e32 v161, 0xffff0000, v112
	v_and_b32_e32 v163, 0xffff0000, v113
	v_lshlrev_b32_e32 v112, 16, v116
	v_and_b32_e32 v113, 0xffff0000, v116
	v_lshlrev_b32_e32 v116, 16, v117
	v_and_b32_e32 v117, 0xffff0000, v117
	v_pk_add_f32 v[112:113], v[160:161], v[112:113]
	v_pk_add_f32 v[116:117], v[162:163], v[116:117]
	v_pk_mul_f32 v[162:163], v[112:113], v[112:113]
	v_pk_mul_f32 v[160:161], v[116:117], v[116:117]
	v_and_b32_e32 v177, 0xffff0000, v98
	v_pk_mov_b32 v[174:175], v[162:163], v[160:161] op_sel:[1,0]
	v_mov_b32_e32 v163, v161
	v_pk_add_f32 v[160:161], v[174:175], v[162:163]
	v_lshlrev_b32_e32 v162, 16, v108
	v_and_b32_e32 v163, 0xffff0000, v108
	v_lshlrev_b32_e32 v108, 16, v109
	v_and_b32_e32 v109, 0xffff0000, v109
	v_lshlrev_b32_e32 v174, 16, v114
	v_and_b32_e32 v175, 0xffff0000, v114
	v_lshlrev_b32_e32 v114, 16, v115
	v_and_b32_e32 v115, 0xffff0000, v115
	v_pk_add_f32 v[114:115], v[108:109], v[114:115]
	v_pk_add_f32 v[162:163], v[162:163], v[174:175]
	v_lshlrev_b32_e32 v108, 16, v106
	v_and_b32_e32 v109, 0xffff0000, v106
	v_lshlrev_b32_e32 v174, 16, v110
	v_and_b32_e32 v175, 0xffff0000, v110
	v_lshlrev_b32_e32 v106, 16, v107
	v_and_b32_e32 v107, 0xffff0000, v107
	v_lshlrev_b32_e32 v110, 16, v111
	v_and_b32_e32 v111, 0xffff0000, v111
	v_pk_add_f32 v[108:109], v[108:109], v[174:175]
	v_pk_add_f32 v[106:107], v[106:107], v[110:111]
	v_mul_f32_e32 v164, v108, v108
	v_mul_f32_e32 v173, v109, v109
	v_pk_add_f32 v[110:111], v[158:159], v[158:159] op_sel:[0,1] op_sel_hi:[1,0]
	v_pk_add_f32 v[158:159], v[160:161], v[160:161] op_sel:[0,1] op_sel_hi:[1,0]
	v_mov_b32_e32 v111, v164
	v_mov_b32_e32 v159, v173
	v_pk_add_f32 v[110:111], v[110:111], v[158:159]
	v_mul_f32_e32 v158, v163, v163
	v_mul_f32_e32 v160, v115, v115
	v_mul_f32_e32 v174, v106, v106
	v_mul_f32_e32 v175, v107, v107
	v_pk_fma_f32 v[158:159], v[162:163], v[162:163], v[158:159] op_sel_hi:[1,1,0]
	v_pk_fma_f32 v[160:161], v[114:115], v[114:115], v[160:161] op_sel_hi:[1,1,0]
	v_mov_b32_e32 v159, v174
	v_mov_b32_e32 v161, v175
	v_pk_add_f32 v[158:159], v[158:159], v[160:161]
	v_lshlrev_b32_e32 v160, 16, v101
	v_pk_add_f32 v[110:111], v[110:111], v[158:159]
	v_lshlrev_b32_e32 v158, 16, v100
	v_and_b32_e32 v159, 0xffff0000, v100
	v_and_b32_e32 v161, 0xffff0000, v101
	v_lshlrev_b32_e32 v100, 16, v104
	v_and_b32_e32 v101, 0xffff0000, v104
	v_lshlrev_b32_e32 v104, 16, v105
	v_and_b32_e32 v105, 0xffff0000, v105
	v_pk_add_f32 v[100:101], v[158:159], v[100:101]
	v_pk_add_f32 v[104:105], v[160:161], v[104:105]
	v_pk_mul_f32 v[160:161], v[100:101], v[100:101]
	v_pk_mul_f32 v[158:159], v[104:105], v[104:105]
	v_lshlrev_b32_e32 v98, 16, v99
	v_pk_mov_b32 v[174:175], v[160:161], v[158:159] op_sel:[1,0]
	v_mov_b32_e32 v161, v159
	v_pk_add_f32 v[174:175], v[174:175], v[160:161]
	v_lshlrev_b32_e32 v158, 16, v96
	v_and_b32_e32 v159, 0xffff0000, v96
	v_lshlrev_b32_e32 v96, 16, v97
	v_and_b32_e32 v97, 0xffff0000, v97
	v_lshlrev_b32_e32 v160, 16, v102
	v_and_b32_e32 v161, 0xffff0000, v102
	v_lshlrev_b32_e32 v102, 16, v103
	v_and_b32_e32 v103, 0xffff0000, v103
	v_pk_add_f32 v[96:97], v[96:97], v[102:103]
	v_pk_add_f32 v[102:103], v[158:159], v[160:161]
	v_lshlrev_b32_e32 v160, 16, v94
	v_and_b32_e32 v161, 0xffff0000, v94
	v_lshlrev_b32_e32 v94, 16, v95
	v_and_b32_e32 v95, 0xffff0000, v95
	v_and_b32_e32 v99, 0xffff0000, v99
	v_pk_add_f32 v[160:161], v[160:161], v[176:177]
	v_pk_add_f32 v[158:159], v[94:95], v[98:99]
	v_mul_f32_e32 v98, v160, v160
	v_pk_add_f32 v[94:95], v[110:111], v[110:111] op_sel:[0,1] op_sel_hi:[1,0]
	v_mul_f32_e32 v164, v161, v161
	v_mov_b32_e32 v95, v98
	v_pk_add_f32 v[98:99], v[174:175], v[174:175] op_sel:[0,1] op_sel_hi:[1,0]
	global_load_dwordx4 v[174:177], v[0:1], off
	v_mov_b32_e32 v99, v164
	v_pk_add_f32 v[94:95], v[94:95], v[98:99]
	v_mul_f32_e32 v98, v103, v103
	v_mul_f32_e32 v110, v97, v97
	v_mul_f32_e32 v173, v158, v158
	v_mul_f32_e32 v178, v159, v159
	v_pk_fma_f32 v[98:99], v[102:103], v[102:103], v[98:99] op_sel_hi:[1,1,0]
	v_pk_fma_f32 v[110:111], v[96:97], v[96:97], v[110:111] op_sel_hi:[1,1,0]
	v_mov_b32_e32 v99, v173
	v_mov_b32_e32 v111, v178
	v_pk_add_f32 v[98:99], v[98:99], v[110:111]
	v_lshl_add_u64 v[28:29], v[28:29], 0, s[6:7]
	v_pk_add_f32 v[94:95], v[94:95], v[98:99]
	s_nop 0
	v_add_f32_e32 v94, v94, v95
	ds_bpermute_b32 v95, v165, v94
	s_waitcnt lgkmcnt(0)
; #define GAS __attribute__((address_space(1)))
; __device__ __forceinline__ float wave_sum(float v) {
; #pragma unroll
;     for (int o = 1; o < 64; o <<= 1) v += __shfl_xor(v, o);
;     return v;
; }
; __global__ void __launch_bounds__(NTHREADS, 2) fwd(Args a) {
;     ...
;             const float rstd = 1.0f / sqrtf(wave_sum(s) * (1.0f / D) + 1e-6f);
; #pragma unroll
;             for (int q = 0; q < 16; ++q) { const f32x4 gg = *(const GAS f32x4*)(fg + 4 * lane + 256 * q); op[64 * q] = v[q] * rstd * gg; }
	v_add_f32_e32 v94, v94, v95
	ds_bpermute_b32 v95, v166, v94
	s_waitcnt lgkmcnt(0)
	v_add_f32_e32 v94, v94, v95
	ds_bpermute_b32 v95, v167, v94
	s_waitcnt lgkmcnt(0)
	v_add_f32_e32 v94, v94, v95
	ds_bpermute_b32 v95, v168, v94
	s_waitcnt lgkmcnt(0)
	v_add_f32_e32 v94, v94, v95
	ds_bpermute_b32 v95, v169, v94
	s_waitcnt lgkmcnt(0)
	v_add_f32_e32 v94, v94, v95
	ds_bpermute_b32 v95, v170, v94
	s_waitcnt lgkmcnt(0)
	v_add_f32_e32 v94, v94, v95
	v_fmamk_f32 v94, v94, 0x39800000, v171
	v_mul_f32_e32 v95, 0x4f800000, v94
	v_cmp_gt_f32_e32 vcc, s11, v94
	s_nop 1
	v_cndmask_b32_e32 v94, v94, v95, vcc
	v_sqrt_f32_e32 v95, v94
	s_nop 0
	v_add_u32_e32 v98, -1, v95
	v_fma_f32 v99, -v98, v95, v94
	v_cmp_ge_f32_e64 s[0:1], 0, v99
	v_add_u32_e32 v99, 1, v95
	s_nop 0
	v_cndmask_b32_e64 v98, v95, v98, s[0:1]
	v_fma_f32 v95, -v99, v95, v94
	v_cmp_lt_f32_e64 s[0:1], 0, v95
	s_nop 1
	v_cndmask_b32_e64 v95, v98, v99, s[0:1]
	v_mul_f32_e32 v98, 0x37800000, v95
	v_cndmask_b32_e32 v95, v95, v98, vcc
	v_cmp_class_f32_e32 vcc, v94, v172
	s_nop 1
	v_cndmask_b32_e32 v94, v95, v94, vcc
	v_div_scale_f32 v95, s[0:1], v94, v94, 1.0
	v_rcp_f32_e32 v98, v95
	s_nop 0
	v_fma_f32 v99, -v95, v98, 1.0
	v_fmac_f32_e32 v98, v99, v98
	v_div_scale_f32 v99, vcc, 1.0, v94, 1.0
	v_mul_f32_e32 v110, v99, v98
	v_fma_f32 v111, -v95, v110, v99
	v_fmac_f32_e32 v110, v111, v98
	v_fma_f32 v95, -v95, v110, v99
	v_div_fmas_f32 v95, v95, v98, v110
	v_div_fixup_f32 v164, v95, v94, 1.0
	v_pk_mul_f32 v[94:95], v[164:165], v[152:153] op_sel_hi:[0,1]
	v_pk_mul_f32 v[98:99], v[164:165], v[154:155] op_sel_hi:[0,1]
	s_waitcnt vmcnt(0)
	v_pk_mul_f32 v[154:155], v[176:177], v[98:99]
	v_pk_mul_f32 v[152:153], v[174:175], v[94:95]
	global_store_dwordx4 v[26:27], v[152:155], off nt
	global_load_dwordx4 v[152:155], v[0:1], off offset:1024
	v_pk_mul_f32 v[94:95], v[164:165], v[156:157] op_sel_hi:[0,1]
	v_pk_mul_f32 v[98:99], v[164:165], v[148:149] op_sel_hi:[0,1]
	v_pk_mul_f32 v[110:111], v[164:165], v[136:137] op_sel_hi:[0,1]
	v_pk_mul_f32 v[124:125], v[164:165], v[124:125] op_sel_hi:[0,1]
	v_pk_mul_f32 v[96:97], v[164:165], v[96:97] op_sel_hi:[0,1]
	v_mov_b64_e32 v[156:157], v[66:67]
	s_waitcnt vmcnt(0)
	v_pk_mul_f32 v[152:153], v[152:153], v[98:99]
	v_pk_mul_f32 v[154:155], v[154:155], v[94:95]
	global_store_dwordx4 v[26:27], v[152:155], off offset:1024 nt
	global_load_dwordx4 v[152:155], v[0:1], off offset:2048
	v_pk_mul_f32 v[94:95], v[164:165], v[144:145] op_sel_hi:[0,1]
	v_pk_mul_f32 v[98:99], v[164:165], v[150:151] op_sel_hi:[0,1]
	s_waitcnt vmcnt(0)
	v_pk_mul_f32 v[148:149], v[152:153], v[98:99]
	v_pk_mul_f32 v[150:151], v[154:155], v[94:95]
	global_store_dwordx4 v[26:27], v[148:151], off offset:2048 nt
	global_load_dwordx4 v[148:151], v[0:1], off offset:3072
	v_pk_mul_f32 v[94:95], v[164:165], v[142:143] op_sel_hi:[0,1]
	v_pk_mul_f32 v[98:99], v[164:165], v[146:147] op_sel_hi:[0,1]
	v_mov_b64_e32 v[152:153], v[30:31]
	v_mov_b64_e32 v[146:147], v[62:63]
	s_waitcnt vmcnt(0)
	v_pk_mul_f32 v[142:143], v[148:149], v[98:99]
	v_pk_mul_f32 v[144:145], v[150:151], v[94:95]
	global_store_dwordx4 v[26:27], v[142:145], off offset:3072 nt
	global_load_dwordx4 v[142:145], v[2:3], off
	v_add_co_u32_e32 v94, vcc, s12, v26
	v_pk_mul_f32 v[98:99], v[164:165], v[140:141] op_sel_hi:[0,1]
	s_nop 0
	v_addc_co_u32_e32 v95, vcc, 0, v27, vcc
	v_mov_b64_e32 v[148:149], v[32:33]
	v_mov_b64_e32 v[150:151], v[64:65]
	s_waitcnt vmcnt(0)
	v_pk_mul_f32 v[140:141], v[142:143], v[110:111]
	v_pk_mul_f32 v[142:143], v[144:145], v[98:99]
	global_store_dwordx4 v[94:95], v[140:143], off offset:-4096 nt
	global_load_dwordx4 v[140:143], v[4:5], off
	v_add_co_u32_e32 v98, vcc, s3, v26
	v_pk_mul_f32 v[110:111], v[164:165], v[132:133] op_sel_hi:[0,1]
	v_pk_mul_f32 v[132:133], v[164:165], v[138:139] op_sel_hi:[0,1]
	v_addc_co_u32_e32 v99, vcc, 0, v27, vcc
	v_add_co_u32_e32 v154, vcc, s13, v26
	v_mov_b64_e32 v[144:145], v[34:35]
	s_nop 0
	v_addc_co_u32_e32 v155, vcc, 0, v27, vcc
	s_andn2_b64 vcc, exec, s[8:9]
	v_lshl_add_u64 v[26:27], v[26:27], 0, s[4:5]
	s_waitcnt vmcnt(0)
; #define GAS __attribute__((address_space(1)))
; __global__ void __launch_bounds__(NTHREADS, 2) fwd(Args a) {
;     ...
;             for (int q = 0; q < 16; ++q) { const f32x4 gg = *(const GAS f32x4*)(fg + 4 * lane + 256 * q); op[64 * q] = v[q] * rstd * gg; }
; #pragma unroll
;             for (int q = 0; q < 16; ++q) { xv[q] = xn[q]; yv[q] = yn[q]; }
;             row = nrow;
	v_pk_mul_f32 v[136:137], v[140:141], v[132:133]
	v_pk_mul_f32 v[138:139], v[142:143], v[110:111]
	global_store_dwordx4 v[98:99], v[136:139], off offset:1024 nt
	global_load_dwordx4 v[136:139], v[6:7], off
	v_pk_mul_f32 v[110:111], v[164:165], v[130:131] op_sel_hi:[0,1]
	v_pk_mul_f32 v[130:131], v[164:165], v[134:135] op_sel_hi:[0,1]
	v_mov_b64_e32 v[142:143], v[36:37]
	v_mov_b64_e32 v[134:135], v[70:71]
	v_mov_b64_e32 v[140:141], v[74:75]
	s_waitcnt vmcnt(0)
	v_pk_mul_f32 v[130:131], v[136:137], v[130:131]
	v_pk_mul_f32 v[132:133], v[138:139], v[110:111]
	global_store_dwordx4 v[98:99], v[130:133], off offset:2048 nt
	global_load_dwordx4 v[130:133], v[8:9], off
	v_pk_mul_f32 v[110:111], v[164:165], v[128:129] op_sel_hi:[0,1]
	v_mov_b64_e32 v[136:137], v[38:39]
	v_mov_b64_e32 v[138:139], v[72:73]
	s_waitcnt vmcnt(0)
	v_pk_mul_f32 v[128:129], v[130:131], v[124:125]
	v_pk_mul_f32 v[130:131], v[132:133], v[110:111]
	global_store_dwordx4 v[98:99], v[128:131], off offset:3072 nt
	global_load_dwordx4 v[128:131], v[10:11], off
	v_pk_mul_f32 v[98:99], v[164:165], v[120:121] op_sel_hi:[0,1]
	v_pk_mul_f32 v[110:111], v[164:165], v[126:127] op_sel_hi:[0,1]
	v_mov_b64_e32 v[132:133], v[40:41]
	s_waitcnt vmcnt(0)
	v_pk_mul_f32 v[124:125], v[128:129], v[110:111]
	v_pk_mul_f32 v[126:127], v[130:131], v[98:99]
	global_store_dwordx4 v[94:95], v[124:127], off nt
	global_load_dwordx4 v[124:127], v[12:13], off
	v_pk_mul_f32 v[98:99], v[164:165], v[118:119] op_sel_hi:[0,1]
	v_pk_mul_f32 v[110:111], v[164:165], v[122:123] op_sel_hi:[0,1]
	v_mov_b64_e32 v[130:131], v[42:43]
	v_mov_b64_e32 v[122:123], v[78:79]
	v_mov_b64_e32 v[128:129], v[84:85]
	s_waitcnt vmcnt(0)
	v_pk_mul_f32 v[118:119], v[124:125], v[110:111]
	v_pk_mul_f32 v[120:121], v[126:127], v[98:99]
	global_store_dwordx4 v[94:95], v[118:121], off offset:1024 nt
	global_load_dwordx4 v[118:121], v[14:15], off
	v_pk_mul_f32 v[98:99], v[164:165], v[116:117] op_sel_hi:[0,1]
	v_pk_mul_f32 v[110:111], v[164:165], v[112:113] op_sel_hi:[0,1]
	v_mov_b64_e32 v[124:125], v[44:45]
	v_mov_b64_e32 v[116:117], v[80:81]
	v_mov_b64_e32 v[126:127], v[76:77]
	s_waitcnt vmcnt(0)
	v_pk_mul_f32 v[110:111], v[118:119], v[110:111]
	v_pk_mul_f32 v[112:113], v[120:121], v[98:99]
	global_store_dwordx4 v[94:95], v[110:113], off offset:2048 nt
	global_load_dwordx4 v[110:113], v[16:17], off
	v_pk_mul_f32 v[98:99], v[164:165], v[114:115] op_sel_hi:[0,1]
	v_pk_mul_f32 v[114:115], v[164:165], v[162:163] op_sel_hi:[0,1]
	v_pk_mul_f32 v[162:163], v[164:165], v[158:159] op_sel_hi:[0,1]
	v_pk_mul_f32 v[158:159], v[164:165], v[160:161] op_sel_hi:[0,1]
	v_mov_b64_e32 v[118:119], v[54:55]
	v_mov_b64_e32 v[120:121], v[46:47]
	s_waitcnt vmcnt(0)
	v_pk_mul_f32 v[110:111], v[110:111], v[114:115]
	v_pk_mul_f32 v[112:113], v[112:113], v[98:99]
	global_store_dwordx4 v[94:95], v[110:113], off offset:3072 nt
	global_load_dwordx4 v[110:113], v[18:19], off
	v_pk_mul_f32 v[94:95], v[164:165], v[106:107] op_sel_hi:[0,1]
	v_pk_mul_f32 v[98:99], v[164:165], v[108:109] op_sel_hi:[0,1]
	v_mov_b64_e32 v[114:115], v[82:83]
	s_waitcnt vmcnt(0)
	v_pk_mul_f32 v[106:107], v[110:111], v[98:99]
	v_pk_mul_f32 v[108:109], v[112:113], v[94:95]
	global_store_dwordx4 v[154:155], v[106:109], off nt
	global_load_dwordx4 v[106:109], v[20:21], off
	v_pk_mul_f32 v[94:95], v[164:165], v[104:105] op_sel_hi:[0,1]
	v_pk_mul_f32 v[98:99], v[164:165], v[100:101] op_sel_hi:[0,1]
	v_mov_b64_e32 v[112:113], v[52:53]
	v_mov_b64_e32 v[104:105], v[90:91]
	v_mov_b64_e32 v[110:111], v[92:93]
	s_waitcnt vmcnt(0)
	v_pk_mul_f32 v[98:99], v[106:107], v[98:99]
	v_pk_mul_f32 v[100:101], v[108:109], v[94:95]
	global_store_dwordx4 v[154:155], v[98:101], off offset:1024 nt
	global_load_dwordx4 v[98:101], v[22:23], off
	v_pk_mul_f32 v[94:95], v[164:165], v[102:103] op_sel_hi:[0,1]
	v_mov_b64_e32 v[106:107], v[48:49]
	v_mov_b64_e32 v[108:109], v[50:51]
	v_mov_b64_e32 v[102:103], v[88:89]
	s_waitcnt vmcnt(0)
	v_pk_mul_f32 v[94:95], v[98:99], v[94:95]
	v_pk_mul_f32 v[96:97], v[100:101], v[96:97]
	global_store_dwordx4 v[154:155], v[94:97], off offset:2048 nt
	global_load_dwordx4 v[174:177], v[24:25], off
	v_mov_b64_e32 v[100:101], v[56:57]
	v_mov_b64_e32 v[94:95], v[60:61]
	v_mov_b64_e32 v[96:97], v[58:59]
	v_mov_b64_e32 v[98:99], v[86:87]
	s_waitcnt vmcnt(0)
	v_pk_mul_f32 v[158:159], v[174:175], v[158:159]
	v_pk_mul_f32 v[160:161], v[176:177], v[162:163]
	global_store_dwordx4 v[154:155], v[158:161], off offset:3072 nt
	v_mov_b64_e32 v[154:155], v[68:69]
	s_cbranch_vccz .LBB0_1274
